# r1/r3 short load chains de-serialized (V staging, rope rows) + final RMSNorm rows loaded in one burst
# speedup vs baseline: 1.0300x; 1.0100x over previous
; __device__ __forceinline__ float ss_rstd(const u64_t* ss, int row) { return __builtin_amdgcn_rsqf((float)ss[row] * (SS_IFX / (float)2048) + 1e-6f); }
; __device__ __forceinline__ int otid() { int t = threadIdx.x; asm volatile("" : "+v"(t)); return t; }
; __device__ __forceinline__ void final_phase(const Args& a) {
;     const int tid = otid(); const int lane = tid & 63, gw = blockIdx.x * NWAVE + (tid >> 6), NGW = gridDim.x * NWAVE;
;     const u64_t* ss = (const u64_t*)(a.ws + WS_SS) + 8 * M;
;     for (int m = gw; m < M; m += NGW) { const float rs = ss_rstd(ss, m); f32x4* xr = (f32x4*)(a.out + (size_t)m * D) + lane; const f32x4* gp = (const f32x4*)a.final_g + lane;
; #pragma unroll
;         for (int j = 0; j < 8; ++j) { const f32x4 v = xr[64 * j]; xr[64 * j] = v * rs * gp[64 * j]; } }
; }
.LBB0_26:
	global_load_dwordx2 v[30:31], v[16:17], off
	v_add_co_u32_e32 v96, vcc, s94, v14
	s_nop 1
	v_addc_co_u32_e32 v97, vcc, 0, v15, vcc
	global_load_dwordx4 v[32:35], v[14:15], off
	global_load_dwordx4 v[36:39], v[14:15], off offset:1024
	global_load_dwordx4 v[40:43], v[14:15], off offset:2048
	global_load_dwordx4 v[44:47], v[14:15], off offset:3072
	global_load_dwordx4 v[48:51], v[96:97], off
	global_load_dwordx4 v[52:55], v[96:97], off offset:1024
	global_load_dwordx4 v[56:59], v[96:97], off offset:2048
	global_load_dwordx4 v[60:63], v[96:97], off offset:3072
	global_load_dwordx4 v[64:67], v[4:5], off
	global_load_dwordx4 v[68:71], v[4:5], off offset:1024
	global_load_dwordx4 v[72:75], v[4:5], off offset:2048
	global_load_dwordx4 v[76:79], v[4:5], off offset:3072
	global_load_dwordx4 v[80:83], v[6:7], off
	global_load_dwordx4 v[84:87], v[8:9], off
	global_load_dwordx4 v[88:91], v[10:11], off
	global_load_dwordx4 v[92:95], v[12:13], off
	v_add_u32_e32 v2, s58, v2
	v_lshl_add_u64 v[16:17], v[16:17], 0, s[14:15]
	s_waitcnt vmcnt(16)
	v_ffbh_u32_e32 v0, v31
	v_min_u32_e32 v0, 32, v0
	v_lshlrev_b64 v[30:31], v0, v[30:31]
	v_min_u32_e32 v3, 1, v30
	v_or_b32_e32 v3, v31, v3
	v_cvt_f32_u32_e32 v3, v3
	v_sub_u32_e32 v0, 32, v0
	v_ldexp_f32 v0, v3, v0
	v_fmamk_f32 v0, v0, 0x2e000000, v207
	v_rsq_f32_e32 v0, v0
	v_cmp_lt_i32_e32 vcc, s75, v2
	s_or_b64 s[10:11], vcc, s[10:11]
	s_waitcnt vmcnt(0)
	v_pk_mul_f32 v[32:33], v[32:33], v[0:1] op_sel_hi:[1,0]
	v_pk_mul_f32 v[34:35], v[34:35], v[0:1] op_sel_hi:[1,0]
	v_pk_mul_f32 v[32:33], v[64:65], v[32:33]
	v_pk_mul_f32 v[34:35], v[66:67], v[34:35]
	global_store_dwordx4 v[14:15], v[32:35], off
	v_pk_mul_f32 v[36:37], v[36:37], v[0:1] op_sel_hi:[1,0]
	v_pk_mul_f32 v[38:39], v[38:39], v[0:1] op_sel_hi:[1,0]
	v_pk_mul_f32 v[36:37], v[68:69], v[36:37]
	v_pk_mul_f32 v[38:39], v[70:71], v[38:39]
	global_store_dwordx4 v[14:15], v[36:39], off offset:1024
	v_pk_mul_f32 v[40:41], v[40:41], v[0:1] op_sel_hi:[1,0]
	v_pk_mul_f32 v[42:43], v[42:43], v[0:1] op_sel_hi:[1,0]
	v_pk_mul_f32 v[40:41], v[72:73], v[40:41]
	v_pk_mul_f32 v[42:43], v[74:75], v[42:43]
	global_store_dwordx4 v[14:15], v[40:43], off offset:2048
	v_pk_mul_f32 v[44:45], v[44:45], v[0:1] op_sel_hi:[1,0]
	v_pk_mul_f32 v[46:47], v[46:47], v[0:1] op_sel_hi:[1,0]
	v_pk_mul_f32 v[44:45], v[76:77], v[44:45]
	v_pk_mul_f32 v[46:47], v[78:79], v[46:47]
	global_store_dwordx4 v[14:15], v[44:47], off offset:3072
	v_pk_mul_f32 v[48:49], v[48:49], v[0:1] op_sel_hi:[1,0]
	v_pk_mul_f32 v[50:51], v[50:51], v[0:1] op_sel_hi:[1,0]
	v_pk_mul_f32 v[48:49], v[80:81], v[48:49]
	v_pk_mul_f32 v[50:51], v[82:83], v[50:51]
	global_store_dwordx4 v[96:97], v[48:51], off
	v_pk_mul_f32 v[52:53], v[52:53], v[0:1] op_sel_hi:[1,0]
	v_pk_mul_f32 v[54:55], v[54:55], v[0:1] op_sel_hi:[1,0]
	v_pk_mul_f32 v[52:53], v[84:85], v[52:53]
	v_pk_mul_f32 v[54:55], v[86:87], v[54:55]
	global_store_dwordx4 v[96:97], v[52:55], off offset:1024
	v_pk_mul_f32 v[56:57], v[56:57], v[0:1] op_sel_hi:[1,0]
	v_pk_mul_f32 v[58:59], v[58:59], v[0:1] op_sel_hi:[1,0]
	v_pk_mul_f32 v[56:57], v[88:89], v[56:57]
	v_pk_mul_f32 v[58:59], v[90:91], v[58:59]
	global_store_dwordx4 v[96:97], v[56:59], off offset:2048
	v_pk_mul_f32 v[60:61], v[60:61], v[0:1] op_sel_hi:[1,0]
	v_pk_mul_f32 v[62:63], v[62:63], v[0:1] op_sel_hi:[1,0]
	v_pk_mul_f32 v[60:61], v[92:93], v[60:61]
	v_pk_mul_f32 v[62:63], v[94:95], v[62:63]
	global_store_dwordx4 v[96:97], v[60:63], off offset:3072
	v_lshl_add_u64 v[14:15], v[14:15], 0, s[60:61]
	s_andn2_b64 exec, exec, s[10:11]
	s_cbranch_execnz .LBB0_26

; #define LAS __attribute__((address_space(3)))
; __device__ __forceinline__ u32x4 pack8(const float (&v)[8]) { u32x4 w; w.x = cvt_pk_bf16(v[0], v[1]); w.y = cvt_pk_bf16(v[2], v[3]); w.z = cvt_pk_bf16(v[4], v[5]); w.w = cvt_pk_bf16(v[6], v[7]); return w; }
; __device__ __forceinline__ void r3_item(const Args& a, int L, int item, LAS unsigned char* lds) {
;     ...
;     { const int mat = tid >> 8, i = (tid >> 2) & 63, g = tid & 3;
;         const int col = mat == 0 ? (hl < 4 ? GQ + hl * 64 : RQ + (hl - 4) * 64) : (hl < 4 ? GK + hl * 64 : RK + (hl - 4) * 64);
;         float va[8], vb[8]; load_qk16(a, proj + (R0 + i) * LD + col, hl, c * 64 + i, g, va, vb);
;         const float sg = mat == 0 ? 1.f : -1.f;
; #pragma unroll
;         for (int dir = 0; dir < 2; ++dir) { float ta[8], tb[8];
; #pragma unroll
;             for (int e = 0; e < 8; ++e) { ta[e] = va[e] * __expf(sg * cum[(dir * 64 + i) * 64 + g * 8 + e]); tb[e] = vb[e] * __expf(sg * cum[(dir * 64 + i) * 64 + 32 + g * 8 + e]); }
;             LAS bf16_t* dst = QK + ((dir * 2 + mat) * 64 + i) * PT;
;             *(LAS u32x4*)(dst + g * 8) = pack8(ta); *(LAS u32x4*)(dst + 32 + g * 8) = pack8(tb); } }
;     { const int j = tid >> 3, vg = tid & 7; const int vcol = hl < 4 ? GV + hl * 128 : RV + (hl - 4) * 128;
;         const bf16_t* vp = proj + (R0 + j) * LD + vcol + vg * 16;
; #pragma unroll
;         for (int q = 0; q < 2; ++q) { const u32x4 w = *(const u32x4*)(vp + q * 8); const int v0 = vg * 16 + q * 8;
;             VT[(v0 + 0) * PT + j] = (bf16_t)(w.x & 0xffff); VT[(v0 + 1) * PT + j] = (bf16_t)(w.x >> 16); VT[(v0 + 2) * PT + j] = (bf16_t)(w.y & 0xffff); VT[(v0 + 3) * PT + j] = (bf16_t)(w.y >> 16);
;             VT[(v0 + 4) * PT + j] = (bf16_t)(w.z & 0xffff); VT[(v0 + 5) * PT + j] = (bf16_t)(w.z >> 16); VT[(v0 + 6) * PT + j] = (bf16_t)(w.w & 0xffff); VT[(v0 + 7) * PT + j] = (bf16_t)(w.w >> 16); } }
.LBB0_116:
	v_lshlrev_b32_e32 v16, 8, v21
	v_lshlrev_b32_e32 v17, 2, v22
	v_add3_u32 v16, 0, v16, v17
	ds_read_b128 v[26:29], v16
	ds_read_b128 v[30:33], v16 offset:16
	ds_read_b128 v[34:37], v16 offset:128
	ds_read_b128 v[38:41], v16 offset:144
	v_lshrrev_b32_e32 v17, 2, v24
	s_mov_b32 s5, 0xfffffc0
	s_waitcnt lgkmcnt(3)
	v_mul_f32_e32 v22, v20, v26
	s_waitcnt lgkmcnt(1)
	v_mul_f32_e32 v26, v20, v35
	v_mul_f32_e32 v26, 0x3fb8aa3b, v26
	v_exp_f32_e32 v26, v26
	v_mul_f32_e32 v23, v20, v34
	v_mul_f32_e32 v25, v20, v27
	v_mul_f32_e32 v27, v20, v36
	v_mul_f32_e32 v34, v11, v26
	v_mul_f32_e32 v26, v20, v28
	v_mul_f32_e32 v28, v20, v29
	v_mul_f32_e32 v29, v20, v37
	v_mul_f32_e32 v26, 0x3fb8aa3b, v26
	v_mul_f32_e32 v27, 0x3fb8aa3b, v27
	v_mul_f32_e32 v28, 0x3fb8aa3b, v28
	v_mul_f32_e32 v29, 0x3fb8aa3b, v29
	v_exp_f32_e32 v26, v26
	v_exp_f32_e32 v27, v27
	v_exp_f32_e32 v28, v28
	v_exp_f32_e32 v29, v29
	v_mul_f32_e32 v35, v14, v26
	v_mul_f32_e32 v36, v8, v27
	v_mul_f32_e32 v27, v15, v28
	v_mul_f32_e32 v37, v9, v29
	v_mul_f32_e32 v26, v20, v30
	s_waitcnt lgkmcnt(0)
	v_mul_f32_e32 v28, v20, v38
	v_mul_f32_e32 v29, v20, v31
	v_mul_f32_e32 v26, 0x3fb8aa3b, v26
	v_mul_f32_e32 v28, 0x3fb8aa3b, v28
	v_mul_f32_e32 v29, 0x3fb8aa3b, v29
	v_exp_f32_e32 v26, v26
	v_exp_f32_e32 v28, v28
	v_exp_f32_e32 v29, v29
	v_mul_f32_e32 v22, 0x3fb8aa3b, v22
	v_mul_f32_e32 v31, v12, v26
	v_mul_f32_e32 v38, v2, v28
	v_mul_f32_e32 v28, v13, v29
	v_mul_f32_e32 v26, v20, v32
	v_mul_f32_e32 v29, v20, v40
	v_mul_f32_e32 v32, v20, v33
	v_mul_f32_e32 v29, 0x3fb8aa3b, v29
	v_mul_f32_e32 v32, 0x3fb8aa3b, v32
	v_mul_f32_e32 v25, 0x3fb8aa3b, v25
	v_mul_f32_e32 v30, v20, v39
	v_mul_f32_e32 v26, 0x3fb8aa3b, v26
	v_exp_f32_e32 v29, v29
	v_exp_f32_e32 v32, v32
	v_mul_f32_e32 v33, v20, v41
	v_exp_f32_e32 v22, v22
	v_mul_f32_e32 v23, 0x3fb8aa3b, v23
	v_exp_f32_e32 v25, v25
	v_mul_f32_e32 v30, 0x3fb8aa3b, v30
	v_exp_f32_e32 v26, v26
	v_mul_f32_e32 v33, 0x3fb8aa3b, v33
	v_exp_f32_e32 v23, v23
	v_exp_f32_e32 v30, v30
	v_exp_f32_e32 v33, v33
	v_and_or_b32 v21, v17, s5, v21
	v_mul_f32_e32 v40, v6, v29
	v_mul_f32_e32 v29, v5, v32
	v_mul_lo_u32 v21, v21, s81
	v_mul_f32_e32 v22, v18, v22
	v_mul_f32_e32 v25, v19, v25
	v_mul_f32_e32 v39, v4, v26
	v_cvt_pk_bf16_f32 v26, v22, v25
	v_cvt_pk_bf16_f32 v27, v35, v27
	v_cvt_pk_bf16_f32 v28, v31, v28
	v_cvt_pk_bf16_f32 v29, v39, v29
	v_add3_u32 v0, 0, v21, v0
	v_mul_f32_e32 v23, v10, v23
	v_mul_f32_e32 v30, v3, v30
	v_mul_f32_e32 v32, v7, v33
	ds_write_b128 v0, v[26:29] offset:51200
	v_cvt_pk_bf16_f32 v26, v23, v34
	v_cvt_pk_bf16_f32 v27, v36, v37
	v_cvt_pk_bf16_f32 v28, v38, v30
	v_cvt_pk_bf16_f32 v29, v40, v32
	ds_write_b128 v0, v[26:29] offset:51264
	ds_read_b128 v[26:29], v16 offset:16384
	ds_read_b128 v[30:33], v16 offset:16400
	ds_read_b128 v[34:37], v16 offset:16512
	ds_read_b128 v[38:41], v16 offset:16528
	v_add_u32_e32 v0, 0xc800, v0
	s_lshl_b32 s5, s28, 7
	s_waitcnt lgkmcnt(3)
	v_mul_f32_e32 v21, v20, v26
	s_waitcnt lgkmcnt(1)
	v_mul_f32_e32 v16, v20, v34
	v_mul_f32_e32 v22, v20, v27
	v_mul_f32_e32 v23, v20, v35
	v_mul_f32_e32 v21, 0x3fb8aa3b, v21
	v_mul_f32_e32 v16, 0x3fb8aa3b, v16
	v_mul_f32_e32 v22, 0x3fb8aa3b, v22
	v_mul_f32_e32 v23, 0x3fb8aa3b, v23
	v_exp_f32_e32 v21, v21
	v_exp_f32_e32 v16, v16
	v_exp_f32_e32 v22, v22
	v_exp_f32_e32 v23, v23
	v_mul_f32_e32 v18, v18, v21
	v_mul_f32_e32 v10, v10, v16
	v_mul_f32_e32 v16, v19, v22
	v_mul_f32_e32 v11, v11, v23
	v_mul_f32_e32 v19, v20, v28
	v_mul_f32_e32 v21, v20, v36
	v_mul_f32_e32 v22, v20, v29
	v_mul_f32_e32 v23, v20, v37
	v_mul_f32_e32 v19, 0x3fb8aa3b, v19
	v_mul_f32_e32 v21, 0x3fb8aa3b, v21
	v_mul_f32_e32 v22, 0x3fb8aa3b, v22
	v_mul_f32_e32 v23, 0x3fb8aa3b, v23
	v_exp_f32_e32 v19, v19
	v_exp_f32_e32 v21, v21
	v_exp_f32_e32 v22, v22
	v_exp_f32_e32 v23, v23
	v_mul_f32_e32 v14, v14, v19
	v_mul_f32_e32 v8, v8, v21
	v_mul_f32_e32 v15, v15, v22
	v_mul_f32_e32 v9, v9, v23
	v_mul_f32_e32 v19, v20, v30
	s_waitcnt lgkmcnt(0)
	v_mul_f32_e32 v21, v20, v38
	v_mul_f32_e32 v22, v20, v31
	v_mul_f32_e32 v23, v20, v39
	v_mul_f32_e32 v19, 0x3fb8aa3b, v19
	v_mul_f32_e32 v21, 0x3fb8aa3b, v21
	v_mul_f32_e32 v22, 0x3fb8aa3b, v22
	v_mul_f32_e32 v23, 0x3fb8aa3b, v23
	v_exp_f32_e32 v19, v19
	v_exp_f32_e32 v21, v21
	v_exp_f32_e32 v22, v22
	v_exp_f32_e32 v23, v23
	v_mul_f32_e32 v12, v12, v19
	v_mul_f32_e32 v19, v2, v21
	v_mul_f32_e32 v13, v13, v22
	v_mul_f32_e32 v21, v3, v23
	v_mul_f32_e32 v2, v20, v32
	v_mul_f32_e32 v3, v20, v40
	v_mul_f32_e32 v22, v20, v33
	v_mul_f32_e32 v20, v20, v41
	v_mul_f32_e32 v2, 0x3fb8aa3b, v2
	v_mul_f32_e32 v3, 0x3fb8aa3b, v3
	v_mul_f32_e32 v22, 0x3fb8aa3b, v22
	v_mul_f32_e32 v20, 0x3fb8aa3b, v20
	v_exp_f32_e32 v2, v2
	v_exp_f32_e32 v3, v3
	v_exp_f32_e32 v22, v22
	v_exp_f32_e32 v20, v20
	v_mul_f32_e32 v23, v4, v2
	v_mul_f32_e32 v6, v6, v3
	v_mul_f32_e32 v5, v5, v22
	v_mul_f32_e32 v7, v7, v20
	v_cvt_pk_bf16_f32 v2, v18, v16
	v_cvt_pk_bf16_f32 v3, v14, v15
	v_cvt_pk_bf16_f32 v4, v12, v13
	v_ashrrev_i32_e32 v20, 3, v24
	v_cvt_pk_bf16_f32 v5, v23, v5
	ds_write_b128 v0, v[2:5] offset:18432
	v_cvt_pk_bf16_f32 v2, v10, v11
	v_cvt_pk_bf16_f32 v3, v8, v9
	v_cvt_pk_bf16_f32 v4, v19, v21
	v_ashrrev_i32_e32 v21, 31, v20
	v_cvt_pk_bf16_f32 v5, v6, v7
	ds_write_b128 v0, v[2:5] offset:18496
	v_lshl_add_u64 v[18:19], s[0:1], 0, v[20:21]
	v_mov_b64_e32 v[2:3], s[22:23]
	s_or_b32 s7, s5, 0xe00
	s_add_i32 s24, s5, 0x1200
	v_mad_u64_u32 v[22:23], s[0:1], v18, s79, v[2:3]
	s_and_b64 s[10:11], s[2:3], exec
	v_mov_b32_e32 v0, v23
	s_cselect_b32 s7, s7, s24
	v_mad_u64_u32 v[2:3], s[0:1], v19, s79, v[0:1]
	v_lshlrev_b32_e32 v0, 4, v24
	v_mov_b32_e32 v23, v2
	s_lshl_b32 s24, s7, 1
	v_and_b32_e32 v21, 0x70, v0
	v_lshl_add_u64 v[2:3], v[22:23], 0, s[24:25]
	v_lshlrev_b32_e32 v0, 1, v21
	v_lshl_add_u64 v[6:7], v[2:3], 0, v[0:1]
	flat_load_dwordx4 v[2:5], v[6:7]
	flat_load_dwordx4 v[112:115], v[6:7] offset:16
	v_mul_u32_u24_e32 v8, 0x90, v21
	v_lshlrev_b32_e32 v9, 1, v20
	v_add3_u32 v8, 0, v8, v9
	s_waitcnt vmcnt(0) lgkmcnt(0)
	ds_write_b16 v8, v2 offset:32768
	ds_write_b16_d16_hi v8, v2 offset:32912
	ds_write_b16 v8, v3 offset:33056
	ds_write_b16_d16_hi v8, v3 offset:33200
	ds_write_b16 v8, v4 offset:33344
	ds_write_b16_d16_hi v8, v4 offset:33488
	ds_write_b16 v8, v5 offset:33632
	ds_write_b16_d16_hi v8, v5 offset:33776
	v_ashrrev_i32_e32 v42, 6, v24
	v_and_b32_e32 v44, 1, v42
	v_and_b32_e32 v66, 31, v24
	v_lshlrev_b32_e32 v45, 5, v44
	v_bfe_u32 v25, v24, 5, 1
	ds_write_b16 v8, v112 offset:33920
	ds_write_b16_d16_hi v8, v112 offset:34064
	ds_write_b16 v8, v113 offset:34208
	ds_write_b16_d16_hi v8, v113 offset:34352
	ds_write_b16 v8, v114 offset:34496
	ds_write_b16_d16_hi v8, v114 offset:34640
	ds_write_b16 v8, v115 offset:34784
	ds_write_b16_d16_hi v8, v115 offset:34928
	v_ashrrev_i32_e32 v43, 8, v24
	s_movk_i32 s0, 0x4800
	v_or_b32_e32 v2, v45, v66
	v_mad_i32_i24 v6, v43, s0, 0
	v_mul_u32_u24_e32 v2, 0x90, v2
	v_lshlrev_b32_e32 v24, 4, v25
	v_add3_u32 v34, v6, v2, v24
	s_waitcnt lgkmcnt(0)
	s_barrier
; #define LAS __attribute__((address_space(3)))
; __device__ __forceinline__ unsigned cvt_pk_bf16(float lo, float hi) { unsigned r; asm volatile("v_cvt_pk_bf16_f32 %0, %1, %2" : "=v"(r) : "v"(lo), "v"(hi)); return r; }
; __device__ __forceinline__ void r3_item(const Args& a, int L, int item, LAS unsigned char* lds) {
;     ...
;     { const int dir = wid >> 2, it = (wid >> 1) & 1, jt = wid & 1; f32x16 sc = f32x16{};
;         const LAS bf16_t* Qt = QK + ((dir * 2 + 0) * 64) * PT; const LAS bf16_t* Kt = QK + ((dir * 2 + 1) * 64) * PT;
; #pragma unroll
;         for (int ks = 0; ks < 4; ++ks) { const bf16x8 av = *(const LAS bf16x8*)(Kt + (jt * 32 + r32) * PT + ks * 16 + hi * 8), bv = *(const LAS bf16x8*)(Qt + (it * 32 + r32) * PT + ks * 16 + hi * 8);
;             sc = __builtin_amdgcn_mfma_f32_32x32x16_bf16(av, bv, sc, 0, 0, 0); }
;         const int i = it * 32 + r32;
; #pragma unroll
;         for (int g4 = 0; g4 < 4; ++g4) { float v[4];
; #pragma unroll
;             for (int e = 0; e < 4; ++e) { const int j = jt * 32 + 8 * g4 + 4 * hi + e; const bool keep = dir == 0 ? (j <= i) : (j >= i); v[e] = keep ? sc[g4 * 4 + e] : 0.f; }
;             u32x2 w; w.x = cvt_pk_bf16(v[0], v[1]); w.y = cvt_pk_bf16(v[2], v[3]);
;             *(LAS u32x2*)(P + (dir * 64 + i) * PT + jt * 32 + 8 * g4 + 4 * hi) = w; } }
	ds_read_b128 v[2:5], v34 offset:60416
	v_and_or_b32 v46, v17, 32, v66
	v_mul_u32_u24_e32 v7, 0x90, v46
	v_add3_u32 v38, v6, v7, v24
	ds_read_b128 v[6:9], v38 offset:51200
	ds_read_b128 v[26:29], v34 offset:60448
	ds_read_b128 v[30:33], v38 offset:51232
	s_waitcnt lgkmcnt(2)
	v_mfma_f32_32x32x16_bf16 v[2:17], v[2:5], v[6:9], 0
	v_lshlrev_b32_e32 v67, 2, v25
	v_readlane_b32 s7, v253, 24
	v_and_b32_e32 v68, 3, v42
	s_lshl_b32 s0, s4, 10
	s_or_b32 s0, s5, s0
	v_lshlrev_b32_e32 v69, 5, v43
	s_or_b32 s0, s0, s6
	s_waitcnt lgkmcnt(0)
	v_mfma_f32_32x32x16_bf16 v[2:17], v[26:29], v[30:33], v[2:17]
	ds_read_b128 v[26:29], v34 offset:60480
	ds_read_b128 v[30:33], v38 offset:51264
	ds_read_b128 v[34:37], v34 offset:60512
	ds_read_b128 v[38:41], v38 offset:51296
	s_ashr_i32 s1, s0, 31
	s_movk_i32 s4, 0x210
	s_waitcnt lgkmcnt(2)
	v_mfma_f32_32x32x16_bf16 v[2:17], v[26:29], v[30:33], v[2:17]
	v_lshl_or_b32 v27, v43, 6, v46
	v_lshlrev_b32_e32 v26, 3, v25
	v_or_b32_e32 v25, v45, v67
	v_mul_lo_u32 v27, v27, s81
	v_add_u32_e32 v27, s7, v27
	v_lshlrev_b32_e32 v28, 6, v44
	v_cmp_le_u32_e32 vcc, v25, v46
	s_waitcnt lgkmcnt(0)
	v_mfma_f32_32x32x16_bf16 v[2:17], v[34:37], v[38:41], v[2:17]
	v_add3_u32 v26, v27, v28, v26
	v_cndmask_b32_e64 v27, 0, 1, vcc
	v_cmp_ge_u32_e32 vcc, v25, v46
	s_nop 1
	v_cndmask_b32_e64 v28, 0, 1, vcc
	v_cndmask_b32_e64 v27, v28, v27, s[38:39]
	v_and_b32_e32 v27, 1, v27
	v_cmp_eq_u32_e32 vcc, 1, v27
	v_or_b32_e32 v27, 1, v25
	s_nop 1
	v_cndmask_b32_e32 v2, 0, v2, vcc
	v_cmp_lt_u32_e32 vcc, v25, v46
	s_nop 1
	v_cndmask_b32_e64 v28, 0, 1, vcc
	v_cmp_ge_u32_e32 vcc, v27, v46
	s_nop 1
	v_cndmask_b32_e64 v27, 0, 1, vcc
	v_cndmask_b32_e64 v27, v27, v28, s[38:39]
	v_and_b32_e32 v27, 1, v27
	v_cmp_eq_u32_e32 vcc, 1, v27
	v_or_b32_e32 v27, 2, v25
	s_nop 0
	v_cndmask_b32_e32 v3, 0, v3, vcc
	v_cmp_le_u32_e32 vcc, v27, v46
	v_cvt_pk_bf16_f32 v2, v2, v3
	s_nop 1
	v_cndmask_b32_e64 v28, 0, 1, vcc
	v_cmp_ge_u32_e32 vcc, v27, v46
	s_nop 1
	v_cndmask_b32_e64 v27, 0, 1, vcc
	v_cndmask_b32_e64 v27, v27, v28, s[38:39]
	v_and_b32_e32 v27, 1, v27
	v_cmp_eq_u32_e32 vcc, 1, v27
	v_or_b32_e32 v27, 3, v25
	s_nop 0
	v_cndmask_b32_e32 v4, 0, v4, vcc
	v_cmp_le_u32_e32 vcc, v27, v46
	s_nop 1
	v_cndmask_b32_e64 v28, 0, 1, vcc
	v_cmp_ge_u32_e32 vcc, v27, v46
	s_nop 1
	v_cndmask_b32_e64 v27, 0, 1, vcc
	v_cndmask_b32_e64 v27, v27, v28, s[38:39]
	v_and_b32_e32 v27, 1, v27
	v_cmp_eq_u32_e32 vcc, 1, v27
	s_nop 1
	v_cndmask_b32_e32 v5, 0, v5, vcc
	v_cvt_pk_bf16_f32 v3, v4, v5
	ds_write_b64 v26, v[2:3]
	v_or_b32_e32 v2, 8, v25
	v_cmp_le_u32_e32 vcc, v2, v46
	s_nop 1
	v_cndmask_b32_e64 v3, 0, 1, vcc
	v_cmp_ge_u32_e32 vcc, v2, v46
	s_nop 1
	v_cndmask_b32_e64 v2, 0, 1, vcc
	v_cndmask_b32_e64 v2, v2, v3, s[38:39]
	v_and_b32_e32 v2, 1, v2
	v_cmp_eq_u32_e32 vcc, 1, v2
	v_or_b32_e32 v3, 9, v25
	s_nop 0
	v_cndmask_b32_e32 v2, 0, v6, vcc
	v_cmp_le_u32_e32 vcc, v3, v46
	s_nop 1
	v_cndmask_b32_e64 v4, 0, 1, vcc
	v_cmp_ge_u32_e32 vcc, v3, v46
	s_nop 1
	v_cndmask_b32_e64 v3, 0, 1, vcc
	v_cndmask_b32_e64 v3, v3, v4, s[38:39]
	v_and_b32_e32 v3, 1, v3
	v_cmp_eq_u32_e32 vcc, 1, v3
	v_or_b32_e32 v4, 10, v25
	s_nop 0
	v_cndmask_b32_e32 v3, 0, v7, vcc
	v_cmp_le_u32_e32 vcc, v4, v46
	v_cvt_pk_bf16_f32 v2, v2, v3
	s_nop 1
	v_cndmask_b32_e64 v5, 0, 1, vcc
	v_cmp_ge_u32_e32 vcc, v4, v46
	s_nop 1
	v_cndmask_b32_e64 v4, 0, 1, vcc
	v_cndmask_b32_e64 v4, v4, v5, s[38:39]
	v_and_b32_e32 v4, 1, v4
	v_cmp_eq_u32_e32 vcc, 1, v4
	v_or_b32_e32 v5, 11, v25
	s_nop 0
	v_cndmask_b32_e32 v4, 0, v8, vcc
	v_cmp_le_u32_e32 vcc, v5, v46
	s_nop 1
	v_cndmask_b32_e64 v6, 0, 1, vcc
	v_cmp_ge_u32_e32 vcc, v5, v46
	s_nop 1
	v_cndmask_b32_e64 v5, 0, 1, vcc
	v_cndmask_b32_e64 v5, v5, v6, s[38:39]
	v_and_b32_e32 v5, 1, v5
	v_cmp_eq_u32_e32 vcc, 1, v5
	s_nop 1
	v_cndmask_b32_e32 v5, 0, v9, vcc
	v_cvt_pk_bf16_f32 v3, v4, v5
	ds_write_b64 v26, v[2:3] offset:16
	v_or_b32_e32 v2, 16, v25
	v_cmp_le_u32_e32 vcc, v2, v46
	s_nop 1
	v_cndmask_b32_e64 v3, 0, 1, vcc
	v_cmp_ge_u32_e32 vcc, v2, v46
	s_nop 1
	v_cndmask_b32_e64 v2, 0, 1, vcc
	v_cndmask_b32_e64 v2, v2, v3, s[38:39]
	v_and_b32_e32 v2, 1, v2
	v_cmp_eq_u32_e32 vcc, 1, v2
	v_or_b32_e32 v3, 17, v25
	s_nop 0
	v_cndmask_b32_e32 v2, 0, v10, vcc
	v_cmp_le_u32_e32 vcc, v3, v46
	s_nop 1
	v_cndmask_b32_e64 v4, 0, 1, vcc
	v_cmp_ge_u32_e32 vcc, v3, v46
	s_nop 1
	v_cndmask_b32_e64 v3, 0, 1, vcc
	v_cndmask_b32_e64 v3, v3, v4, s[38:39]
	v_and_b32_e32 v3, 1, v3
	v_cmp_eq_u32_e32 vcc, 1, v3
	v_or_b32_e32 v4, 18, v25
	s_nop 0
	v_cndmask_b32_e32 v3, 0, v11, vcc
	v_cmp_le_u32_e32 vcc, v4, v46
	v_cvt_pk_bf16_f32 v2, v2, v3
	s_nop 1
	v_cndmask_b32_e64 v5, 0, 1, vcc
	v_cmp_ge_u32_e32 vcc, v4, v46
	s_nop 1
	v_cndmask_b32_e64 v4, 0, 1, vcc
	v_cndmask_b32_e64 v4, v4, v5, s[38:39]
	v_and_b32_e32 v4, 1, v4
	v_cmp_eq_u32_e32 vcc, 1, v4
	v_or_b32_e32 v5, 19, v25
	s_nop 0
	v_cndmask_b32_e32 v4, 0, v12, vcc
	v_cmp_le_u32_e32 vcc, v5, v46
	s_nop 1
	v_cndmask_b32_e64 v6, 0, 1, vcc
	v_cmp_ge_u32_e32 vcc, v5, v46
	s_nop 1
	v_cndmask_b32_e64 v5, 0, 1, vcc
	v_cndmask_b32_e64 v5, v5, v6, s[38:39]
	v_and_b32_e32 v5, 1, v5
	v_cmp_eq_u32_e32 vcc, 1, v5
	s_nop 1
	v_cndmask_b32_e32 v5, 0, v13, vcc
	v_cvt_pk_bf16_f32 v3, v4, v5
	ds_write_b64 v26, v[2:3] offset:32
	v_or_b32_e32 v2, 24, v25
	v_cmp_le_u32_e32 vcc, v2, v46
	s_nop 1
	v_cndmask_b32_e64 v3, 0, 1, vcc
	v_cmp_ge_u32_e32 vcc, v2, v46
	s_nop 1
	v_cndmask_b32_e64 v2, 0, 1, vcc
	v_cndmask_b32_e64 v2, v2, v3, s[38:39]
	v_and_b32_e32 v2, 1, v2
	v_cmp_eq_u32_e32 vcc, 1, v2
	v_or_b32_e32 v3, 25, v25
	s_nop 0
	v_cndmask_b32_e32 v2, 0, v14, vcc
	v_cmp_le_u32_e32 vcc, v3, v46
	s_nop 1
	v_cndmask_b32_e64 v4, 0, 1, vcc
	v_cmp_ge_u32_e32 vcc, v3, v46
	s_nop 1
	v_cndmask_b32_e64 v3, 0, 1, vcc
	v_cndmask_b32_e64 v3, v3, v4, s[38:39]
	v_and_b32_e32 v3, 1, v3
	v_cmp_eq_u32_e32 vcc, 1, v3
	v_or_b32_e32 v4, 26, v25
	s_nop 0
	v_cndmask_b32_e32 v3, 0, v15, vcc
	v_cmp_le_u32_e32 vcc, v4, v46
	v_cvt_pk_bf16_f32 v2, v2, v3
	s_nop 1
	v_cndmask_b32_e64 v5, 0, 1, vcc
	v_cmp_ge_u32_e32 vcc, v4, v46
	s_nop 1
	v_cndmask_b32_e64 v4, 0, 1, vcc
	v_cndmask_b32_e64 v4, v4, v5, s[38:39]
	v_and_b32_e32 v4, 1, v4
	v_cmp_eq_u32_e32 vcc, 1, v4
	v_or_b32_e32 v5, 27, v25
	v_mov_b32_e32 v25, v1
	v_cndmask_b32_e32 v4, 0, v16, vcc
	v_cmp_le_u32_e32 vcc, v5, v46
	s_nop 1
	v_cndmask_b32_e64 v6, 0, 1, vcc
	v_cmp_ge_u32_e32 vcc, v5, v46
	s_nop 1
	v_cndmask_b32_e64 v5, 0, 1, vcc
	v_cndmask_b32_e64 v5, v5, v6, s[38:39]
	v_and_b32_e32 v5, 1, v5
	v_cmp_eq_u32_e32 vcc, 1, v5
	v_lshl_or_b32 v6, v68, 5, v66
	v_mul_u32_u24_e32 v6, 0x90, v6
	v_cndmask_b32_e32 v5, 0, v17, vcc
	v_cvt_pk_bf16_f32 v3, v4, v5
	ds_write_b64 v26, v[2:3] offset:48
	v_lshlrev_b32_e32 v2, 7, v66
	v_lshl_or_b32 v2, v68, 12, v2
	v_mov_b32_e32 v3, v1
	v_lshl_add_u64 v[2:3], s[8:9], 0, v[2:3]
	v_lshl_add_u64 v[62:63], v[2:3], 0, v[24:25]
	v_or_b32_e32 v2, v69, v66
	v_mul_lo_u32 v25, v2, s81
	v_add3_u32 v70, s7, v24, v25
	s_lshl_b64 s[6:7], s[0:1], 14
	v_add3_u32 v50, 0, v6, v24
	v_lshl_add_u64 v[64:65], v[62:63], 0, s[6:7]
	s_waitcnt lgkmcnt(0)
	s_barrier
; #define LAS __attribute__((address_space(3)))
; __device__ __forceinline__ int crow(int r, int hi) { return (r & 3) + 8 * (r >> 2) + 4 * hi; }
; __device__ __forceinline__ int crow(int r, int hi) { return (r & 3) + 8 * (r >> 2) + 4 * hi; }
; __device__ __forceinline__ int seqidx(int b, int hl, int dir, int c) { return ((b * 8 + hl) * 2 + dir) * 64 + c; }
; __device__ __forceinline__ void r3_item(const Args& a, int L, int item, LAS unsigned char* lds) {
;     ...
;     { const int it = wid >> 2, vt = wid & 3; f32x16 acc = f32x16{};
;         bf16x8 stf[2][4];
; #pragma unroll
;         for (int dir = 0; dir < 2; ++dir) { const bf16_t* stp = (const bf16_t*)(a.ws + WS_ST) + (size_t)seqidx(b, hl, dir, c) * 8192 + (vt * 32 + r32) * 64 + hi * 8;
; #pragma unroll
;             for (int ks = 0; ks < 4; ++ks) stf[dir][ks] = *(const bf16x8*)(stp + ks * 16); }
; #pragma unroll
;         for (int dir = 0; dir < 2; ++dir) { const LAS bf16_t* Qt = QK + ((dir * 2 + 0) * 64) * PT;
; #pragma unroll
;             for (int ks = 0; ks < 4; ++ks) { const bf16x8 av = *(const LAS bf16x8*)(P + (dir * 64 + it * 32 + r32) * PT + ks * 16 + hi * 8), bv = *(const LAS bf16x8*)(VT + (vt * 32 + r32) * PT + ks * 16 + hi * 8);
;                 acc = __builtin_amdgcn_mfma_f32_32x32x16_bf16(av, bv, acc, 0, 0, 0); }
; #pragma unroll
;             for (int ks = 0; ks < 4; ++ks) { const bf16x8 av = *(const LAS bf16x8*)(Qt + (it * 32 + r32) * PT + ks * 16 + hi * 8), bv = stf[dir][ks];
;                 acc = __builtin_amdgcn_mfma_f32_32x32x16_bf16(av, bv, acc, 0, 0, 0); } }
;         __syncthreads();
;         LAS float* OL = (LAS float*)(lds + L_OL);
; #pragma unroll
;         for (int r = 0; r < 16; ++r) OL[(it * 32 + crow(r, hi)) * OLP + vt * 32 + r32] = acc[r]; }
;     __syncthreads();
;     { const int row = tid >> 3, seg = tid & 7; const LAS float* op = (const LAS float*)(lds + L_OL) + row * OLP + seg * 16; float ov[16]; float s = 0.f;
; #pragma unroll
;         for (int e = 0; e < 16; ++e) { ov[e] = op[e]; s += ov[e] * ov[e]; }
;         s += __shfl_xor(s, 1); s += __shfl_xor(s, 2); s += __shfl_xor(s, 4);
	ds_read_b128 v[2:5], v70
	ds_read_b128 v[26:29], v50 offset:32768
	ds_read_b128 v[30:33], v70 offset:32
	ds_read_b128 v[34:37], v50 offset:32800
	flat_load_dwordx4 v[38:41], v[64:65]
	s_waitcnt lgkmcnt(0)
	v_mfma_f32_32x32x16_bf16 v[2:17], v[2:5], v[26:29], 0
	v_add3_u32 v71, 0, v25, v24
	s_or_b32 s0, s0, 64
	s_ashr_i32 s1, s0, 31
	s_lshl_b64 s[0:1], s[0:1], 14
	v_mfma_f32_32x32x16_bf16 v[2:17], v[30:33], v[34:37], v[2:17]
	ds_read_b128 v[30:33], v70 offset:64
	ds_read_b128 v[42:45], v50 offset:32832
	ds_read_b128 v[46:49], v70 offset:96
	ds_read_b128 v[50:53], v50 offset:32864
	ds_read_b128 v[54:57], v71 offset:51200
	ds_read_b128 v[58:61], v71 offset:51232
	s_waitcnt lgkmcnt(0)
	v_mfma_f32_32x32x16_bf16 v[2:17], v[30:33], v[42:45], v[2:17]
	flat_load_dwordx4 v[30:33], v[64:65] offset:32
	v_mfma_f32_32x32x16_bf16 v[2:17], v[46:49], v[50:53], v[2:17]
	flat_load_dwordx4 v[46:49], v[64:65] offset:64
	s_waitcnt vmcnt(0)
	v_mfma_f32_32x32x16_bf16 v[2:17], v[54:57], v[38:41], v[2:17]
	flat_load_dwordx4 v[38:41], v[64:65] offset:96
	s_waitcnt lgkmcnt(0)
	v_mfma_f32_32x32x16_bf16 v[2:17], v[58:61], v[30:33], v[2:17]
	ds_read_b128 v[30:33], v71 offset:51264
	ds_read_b128 v[54:57], v71 offset:51296
	s_waitcnt lgkmcnt(0)
	v_mfma_f32_32x32x16_bf16 v[2:17], v[30:33], v[46:49], v[2:17]
	ds_read_b128 v[30:33], v70 offset:9216
	v_lshl_add_u64 v[46:47], v[62:63], 0, s[0:1]
	s_and_b64 s[0:1], s[2:3], exec
	s_movk_i32 s0, 0x1400
	s_cselect_b32 s0, 0x1000, s0
	s_or_b32 s0, s0, s5
	s_waitcnt vmcnt(0)
	v_mfma_f32_32x32x16_bf16 v[2:17], v[54:57], v[38:41], v[2:17]
	ds_read_b128 v[38:41], v70 offset:9248
	s_waitcnt lgkmcnt(1)
	v_mfma_f32_32x32x16_bf16 v[2:17], v[30:33], v[26:29], v[2:17]
	flat_load_dwordx4 v[24:27], v[46:47]
	s_waitcnt lgkmcnt(0)
	v_mfma_f32_32x32x16_bf16 v[2:17], v[38:41], v[34:37], v[2:17]
	ds_read_b128 v[28:31], v70 offset:9280
	ds_read_b128 v[32:35], v70 offset:9312
	s_waitcnt lgkmcnt(0)
	v_mfma_f32_32x32x16_bf16 v[2:17], v[28:31], v[42:45], v[2:17]
	flat_load_dwordx4 v[28:31], v[46:47] offset:32
	v_add_u32_e32 v44, 0xc800, v71
	ds_read_b128 v[36:39], v44 offset:18432
	ds_read_b128 v[40:43], v44 offset:18464
	v_mfma_f32_32x32x16_bf16 v[2:17], v[32:35], v[50:53], v[2:17]
	flat_load_dwordx4 v[32:35], v[46:47] offset:64
	s_waitcnt vmcnt(0) lgkmcnt(0)
	v_mfma_f32_32x32x16_bf16 v[2:17], v[36:39], v[24:27], v[2:17]
	flat_load_dwordx4 v[24:27], v[46:47] offset:96
	v_mfma_f32_32x32x16_bf16 v[2:17], v[40:43], v[28:31], v[2:17]
	ds_read_b128 v[28:31], v44 offset:18496
	ds_read_b128 v[36:39], v44 offset:18528
	s_waitcnt lgkmcnt(0)
	s_barrier
	v_mfma_f32_32x32x16_bf16 v[2:17], v[28:31], v[32:35], v[2:17]
	s_waitcnt vmcnt(0)
	v_mfma_f32_32x32x16_bf16 v[2:17], v[36:39], v[24:27], v[2:17]
	v_or_b32_e32 v24, v67, v69
	v_lshl_add_u32 v25, v68, 7, 0
	v_lshlrev_b32_e32 v26, 2, v66
	v_mul_lo_u32 v24, v24, s4
	v_add3_u32 v24, v25, v26, v24
	v_add_u32_e32 v25, 0xc800, v24
	s_nop 5
	ds_write2_b32 v25, v2, v3 offset1:132
	v_add_u32_e32 v2, 0xcc00, v24
	ds_write2_b32 v2, v4, v5 offset0:8 offset1:140
	v_add_u32_e32 v2, 0xd800, v24
	ds_write2_b32 v2, v6, v7 offset0:32 offset1:164
	v_add_u32_e32 v2, 0xdc00, v24
	ds_write2_b32 v2, v8, v9 offset0:40 offset1:172
	v_add_u32_e32 v2, 0xe800, v24
	ds_write2_b32 v2, v10, v11 offset0:64 offset1:196
	v_add_u32_e32 v2, 0xec00, v24
	ds_write2_b32 v2, v12, v13 offset0:72 offset1:204
	v_add_u32_e32 v2, 0xf800, v24
	ds_write2_b32 v2, v14, v15 offset0:96 offset1:228
	v_add_u32_e32 v2, 0xfc00, v24
	ds_write2_b32 v2, v16, v17 offset0:104 offset1:236
	v_or_b32_e32 v2, s0, v21
	v_lshlrev_b32_e32 v2, 1, v2
	v_mov_b32_e32 v3, v1
	v_lshl_add_u64 v[2:3], v[22:23], 0, v[2:3]
	s_waitcnt lgkmcnt(0)
	s_barrier
	flat_load_dwordx4 v[22:25], v[2:3]
	s_lshl_b32 s0, s28, 9
	s_add_u32 s0, s12, s0
	v_mul_lo_u32 v4, v20, s4
	v_lshlrev_b32_e32 v20, 2, v21
	s_addc_u32 s1, s13, 0
	v_mov_b32_e32 v21, v1
	v_add3_u32 v4, 0, v4, v20
	v_lshl_add_u64 v[38:39], s[0:1], 0, v[20:21]
	ds_read_b128 v[14:17], v4 offset:51200
	ds_read_b128 v[10:13], v4 offset:51216
	flat_load_dwordx4 v[26:29], v[2:3] offset:16
	ds_read_b128 v[6:9], v4 offset:51232
	ds_read_b128 v[2:5], v4 offset:51248
	flat_load_dwordx4 v[30:33], v[38:39]
	s_waitcnt lgkmcnt(0)
	v_mul_f32_e32 v34, v15, v15
	v_fmac_f32_e32 v34, v14, v14
	v_fmac_f32_e32 v34, v16, v16
	v_fmac_f32_e32 v34, v17, v17
	v_fmac_f32_e32 v34, v10, v10
	v_fmac_f32_e32 v34, v11, v11
	v_fmac_f32_e32 v34, v12, v12
	v_fmac_f32_e32 v34, v13, v13
	v_pk_mul_f32 v[20:21], v[6:7], v[6:7]
	s_lshl_b32 s24, s28, 8
	v_add_f32_e32 v20, v34, v20
	v_add_f32_e32 v34, v20, v21
	v_pk_mul_f32 v[20:21], v[8:9], v[8:9]
	s_mov_b64 s[0:1], 0x21300800
	v_add_f32_e32 v20, v34, v20
	v_add_f32_e32 v34, v20, v21
	v_pk_mul_f32 v[20:21], v[2:3], v[2:3]
	s_add_i32 s15, s15, s87
	v_add_f32_e32 v20, v34, v20
	v_add_f32_e32 v34, v20, v21
	v_pk_mul_f32 v[20:21], v[4:5], v[4:5]
	s_add_i32 s14, s14, s87
	v_add_f32_e32 v20, v34, v20
	v_and_b32_e32 v34, 64, v208
	v_add_f32_e32 v20, v20, v21
	v_xor_b32_e32 v21, 1, v208
	v_add_u32_e32 v40, 64, v34
	v_cmp_lt_i32_e32 vcc, v21, v40
	flat_load_dwordx4 v[34:37], v[38:39] offset:16
	s_cmpk_gt_i32 s15, 0x3ff
	v_cndmask_b32_e32 v21, v208, v21, vcc
	v_lshlrev_b32_e32 v21, 2, v21
	ds_bpermute_b32 v21, v21, v20
	s_waitcnt lgkmcnt(0)
	v_add_f32_e32 v20, v20, v21
	v_xor_b32_e32 v21, 2, v208
	v_cmp_lt_i32_e32 vcc, v21, v40
	s_waitcnt vmcnt(0)
; #define LAS __attribute__((address_space(3)))
; __device__ __forceinline__ unsigned cvt_pk_bf16(float lo, float hi) { unsigned r; asm volatile("v_cvt_pk_bf16_f32 %0, %1, %2" : "=v"(r) : "v"(lo), "v"(hi)); return r; }
; __device__ __forceinline__ float siluf(float x) { return x * __builtin_amdgcn_rcpf(1.f + __expf(-x)); }
; __device__ __forceinline__ void r3_item(const Args& a, int L, int item, LAS unsigned char* lds) {
;     ...
;     { const int row = tid >> 3, seg = tid & 7; const LAS float* op = (const LAS float*)(lds + L_OL) + row * OLP + seg * 16; float ov[16]; float s = 0.f;
; #pragma unroll
;         for (int e = 0; e < 16; ++e) { ov[e] = op[e]; s += ov[e] * ov[e]; }
;         s += __shfl_xor(s, 1); s += __shfl_xor(s, 2); s += __shfl_xor(s, 4);
;         const float rs = rsqrtf(s * (1.0f / 128.0f) + EPS);
;         const int gcol = (hl < 4 ? GR + hl * 128 : RG + (hl - 4) * 128) + seg * 16;
;         const bf16_t* gp = proj + (R0 + row) * LD + gcol; const u32x4 g0 = *(const u32x4*)gp, g1 = *(const u32x4*)(gp + 8);
;         float gt[16] = {bflo(g0.x), bfhi(g0.x), bflo(g0.y), bfhi(g0.y), bflo(g0.z), bfhi(g0.z), bflo(g0.w), bfhi(g0.w), bflo(g1.x), bfhi(g1.x), bflo(g1.y), bfhi(g1.y), bflo(g1.z), bfhi(g1.z), bflo(g1.w), bfhi(g1.w)};
;         const float* hg = a.head_gain + (size_t)L * D + 1024 + hl * 128 + seg * 16;
;         float res[16];
; #pragma unroll
;         for (int e = 0; e < 16; ++e) res[e] = ov[e] * rs * hg[e] * siluf(gt[e]);
;         bf16_t* mp = (bf16_t*)(a.ws + WS_MRG) + (R0 + row) * D + 1024 + hl * 128 + seg * 16;
;         u32x4 w0, w1; w0.x = cvt_pk_bf16(res[0], res[1]); w0.y = cvt_pk_bf16(res[2], res[3]); w0.z = cvt_pk_bf16(res[4], res[5]); w0.w = cvt_pk_bf16(res[6], res[7]);
;         w1.x = cvt_pk_bf16(res[8], res[9]); w1.y = cvt_pk_bf16(res[10], res[11]); w1.z = cvt_pk_bf16(res[12], res[13]); w1.w = cvt_pk_bf16(res[14], res[15]);
;         *(u32x4*)mp = w0; *(u32x4*)(mp + 8) = w1; }
	v_and_b32_e32 v42, 0xffff0000, v22
	v_cndmask_b32_e32 v21, v208, v21, vcc
	v_lshlrev_b32_e32 v21, 2, v21
	ds_bpermute_b32 v21, v21, v20
	v_lshlrev_b32_e32 v44, 16, v23
	v_and_b32_e32 v46, 0xffff0000, v23
	v_lshlrev_b32_e32 v48, 16, v24
	v_and_b32_e32 v50, 0xffff0000, v24
	s_waitcnt lgkmcnt(0)
	v_add_f32_e32 v20, v20, v21
	v_xor_b32_e32 v21, 4, v208
	v_cmp_lt_i32_e32 vcc, v21, v40
	v_lshlrev_b32_e32 v40, 16, v22
	v_mul_f32_e32 v24, 0xbfb8aa3b, v40
	v_cndmask_b32_e32 v21, v208, v21, vcc
	v_lshlrev_b32_e32 v21, 2, v21
	ds_bpermute_b32 v21, v21, v20
	v_exp_f32_e32 v24, v24
	v_lshlrev_b32_e32 v52, 16, v25
	v_and_b32_e32 v54, 0xffff0000, v25
	v_mov_b32_e32 v25, v30
	s_waitcnt lgkmcnt(0)
	v_add_f32_e32 v20, v20, v21
	v_fmamk_f32 v20, v20, 0x3c000000, v207
	v_mul_f32_e32 v21, 0x4b800000, v20
	v_cmp_gt_f32_e32 vcc, s34, v20
	v_lshlrev_b32_e32 v56, 16, v26
	v_and_b32_e32 v58, 0xffff0000, v26
	v_cndmask_b32_e32 v20, v20, v21, vcc
	v_rsq_f32_e32 v20, v20
	v_lshlrev_b32_e32 v60, 16, v27
	v_and_b32_e32 v62, 0xffff0000, v27
	v_lshlrev_b32_e32 v64, 16, v28
	v_mul_f32_e32 v21, 0x45800000, v20
	v_cndmask_b32_e32 v69, v20, v21, vcc
	flat_load_dwordx4 v[20:23], v[38:39] offset:32
	v_mul_f32_e32 v41, v14, v69
	v_add_f32_e32 v14, 1.0, v24
	v_rcp_f32_e32 v24, v14
	v_mul_f32_e32 v14, 0xbfb8aa3b, v42
	v_exp_f32_e32 v14, v14
	v_mul_f32_e32 v43, v15, v69
	v_pk_mul_f32 v[24:25], v[24:25], v[40:41]
	v_mul_f32_e32 v45, v16, v69
	v_add_f32_e32 v14, 1.0, v14
	v_rcp_f32_e32 v30, v14
	v_mul_f32_e32 v14, 0xbfb8aa3b, v44
	v_mul_f32_e32 v40, v24, v25
	v_exp_f32_e32 v24, v14
	v_pk_mul_f32 v[14:15], v[30:31], v[42:43]
	v_mul_f32_e32 v47, v17, v69
	v_mul_f32_e32 v30, v14, v15
	v_add_f32_e32 v14, 1.0, v24
	flat_load_dwordx4 v[24:27], v[38:39] offset:48
	v_rcp_f32_e32 v14, v14
	v_mul_f32_e32 v15, 0xbfb8aa3b, v46
	v_exp_f32_e32 v16, v15
	v_mov_b32_e32 v15, v32
	v_pk_mul_f32 v[14:15], v[14:15], v[44:45]
	v_mul_f32_e32 v49, v10, v69
	v_mul_f32_e32 v31, v14, v15
	v_add_f32_e32 v14, 1.0, v16
	v_rcp_f32_e32 v32, v14
	v_mul_f32_e32 v14, 0xbfb8aa3b, v48
	v_exp_f32_e32 v16, v14
	v_mul_f32_e32 v51, v11, v69
	v_pk_mul_f32 v[14:15], v[32:33], v[46:47]
	v_mul_f32_e32 v53, v12, v69
	v_add_f32_e32 v10, 1.0, v16
	v_mul_f32_e32 v17, v14, v15
	v_rcp_f32_e32 v14, v10
	v_mul_f32_e32 v10, 0xbfb8aa3b, v50
	v_exp_f32_e32 v10, v10
	v_mov_b32_e32 v15, v34
	v_pk_mul_f32 v[14:15], v[14:15], v[48:49]
	v_mul_f32_e32 v12, 0xbfb8aa3b, v54
	v_add_f32_e32 v10, 1.0, v10
	v_rcp_f32_e32 v34, v10
	v_mul_f32_e32 v10, 0xbfb8aa3b, v52
	v_mul_f32_e32 v14, v14, v15
	v_exp_f32_e32 v15, v10
	v_pk_mul_f32 v[10:11], v[34:35], v[50:51]
	v_exp_f32_e32 v12, v12
	v_mul_f32_e32 v16, v10, v11
	v_add_f32_e32 v10, 1.0, v15
	v_rcp_f32_e32 v10, v10
	v_mov_b32_e32 v11, v36
	v_mov_b32_e32 v55, v37
	v_mul_f32_e32 v7, v7, v69
	v_pk_mul_f32 v[10:11], v[10:11], v[52:53]
	v_and_b32_e32 v28, 0xffff0000, v28
	v_mul_f32_e32 v15, v10, v11
	v_add_f32_e32 v10, 1.0, v12
	v_rcp_f32_e32 v10, v10
	v_mul_f32_e32 v12, 0xbfb8aa3b, v56
	v_exp_f32_e32 v12, v12
	v_mul_f32_e32 v11, v13, v69
	v_pk_mul_f32 v[10:11], v[10:11], v[54:55]
	v_lshlrev_b32_e32 v66, 16, v29
	v_mul_f32_e32 v32, v10, v11
	v_mul_f32_e32 v11, v6, v69
	v_add_f32_e32 v6, 1.0, v12
	v_rcp_f32_e32 v10, v6
	v_mul_f32_e32 v6, 0xbfb8aa3b, v58
	v_exp_f32_e32 v6, v6
	v_and_b32_e32 v68, 0xffff0000, v29
	v_mul_f32_e32 v3, v3, v69
	v_mul_f32_e32 v5, v5, v69
	v_add_f32_e32 v6, 1.0, v6
	v_rcp_f32_e32 v6, v6
	s_waitcnt vmcnt(0) lgkmcnt(0)
	v_mov_b32_e32 v57, v20
	v_pk_mul_f32 v[10:11], v[10:11], v[56:57]
	v_mov_b32_e32 v59, v21
	v_mul_f32_e32 v20, v10, v11
	v_mul_f32_e32 v10, 0xbfb8aa3b, v60
	v_exp_f32_e32 v10, v10
	v_pk_mul_f32 v[6:7], v[6:7], v[58:59]
	v_mov_b32_e32 v61, v22
	v_mul_f32_e32 v21, v6, v7
	v_add_f32_e32 v6, 1.0, v10
	v_mul_f32_e32 v7, v8, v69
	v_rcp_f32_e32 v6, v6
	v_mul_f32_e32 v8, 0xbfb8aa3b, v62
	v_exp_f32_e32 v8, v8
	v_mov_b32_e32 v63, v23
	v_pk_mul_f32 v[6:7], v[6:7], v[60:61]
	v_mov_b32_e32 v65, v24
	v_mul_f32_e32 v22, v6, v7
	v_add_f32_e32 v6, 1.0, v8
	v_rcp_f32_e32 v6, v6
	v_mul_f32_e32 v8, 0xbfb8aa3b, v64
	v_exp_f32_e32 v8, v8
	v_mul_f32_e32 v7, v9, v69
	v_pk_mul_f32 v[6:7], v[6:7], v[62:63]
	v_mov_b32_e32 v29, v25
	v_mul_f32_e32 v9, v6, v7
	v_mul_f32_e32 v7, v2, v69
	v_add_f32_e32 v2, 1.0, v8
	v_rcp_f32_e32 v6, v2
	v_mul_f32_e32 v2, 0xbfb8aa3b, v28
	v_exp_f32_e32 v2, v2
	v_mov_b32_e32 v67, v26
	v_pk_mul_f32 v[6:7], v[6:7], v[64:65]
	v_add_f32_e32 v2, 1.0, v2
	v_rcp_f32_e32 v2, v2
	v_mul_f32_e32 v8, v6, v7
	v_mul_f32_e32 v6, 0xbfb8aa3b, v66
	v_exp_f32_e32 v6, v6
	v_pk_mul_f32 v[2:3], v[2:3], v[28:29]
	s_nop 0
	v_mul_f32_e32 v23, v2, v3
	v_mul_f32_e32 v3, 0xbfb8aa3b, v68
	v_add_f32_e32 v2, 1.0, v6
	v_exp_f32_e32 v6, v3
	v_rcp_f32_e32 v2, v2
	v_mul_f32_e32 v3, v4, v69
	v_mov_b32_e32 v69, v27
	v_add_f32_e32 v4, 1.0, v6
	v_rcp_f32_e32 v4, v4
	v_pk_mul_f32 v[2:3], v[2:3], v[66:67]
	s_nop 0
	v_mul_f32_e32 v24, v2, v3
	v_pk_mul_f32 v[2:3], v[4:5], v[68:69]
	s_nop 0
	v_mul_f32_e32 v25, v2, v3
	v_lshlrev_b64 v[2:3], 12, v[18:19]
	v_lshl_add_u64 v[2:3], s[98:99], 0, v[2:3]
	v_lshl_add_u64 v[2:3], v[2:3], 0, s[24:25]
	v_lshl_add_u64 v[10:11], v[2:3], 0, v[0:1]
	v_lshl_add_u64 v[12:13], v[10:11], 0, s[0:1]
	v_add_co_u32_e32 v10, vcc, 0x21300000, v10
	v_cvt_pk_bf16_f32 v2, v40, v30
	v_cvt_pk_bf16_f32 v3, v31, v17
	v_cvt_pk_bf16_f32 v4, v14, v16
	v_cvt_pk_bf16_f32 v5, v15, v32
	s_nop 1
	v_addc_co_u32_e32 v11, vcc, 0, v11, vcc
	v_cvt_pk_bf16_f32 v6, v20, v21
	v_cvt_pk_bf16_f32 v7, v22, v9
	v_cvt_pk_bf16_f32 v8, v8, v23
	v_cvt_pk_bf16_f32 v9, v24, v25
	flat_store_dwordx4 v[10:11], v[2:5] offset:2048
	flat_store_dwordx4 v[12:13], v[6:9] offset:16
	s_cbranch_scc1 .LBB0_144

; __device__ __forceinline__ void load_qk16(const Args& a, const bf16_t* __restrict__ src, int hl, int pos, int g, float (&va)[8], float (&vb)[8]) {
;     const u32x4 wa = *(const u32x4*)(src + g * 8), wb = *(const u32x4*)(src + 32 + g * 8);
;     va[0] = bflo(wa.x); va[1] = bfhi(wa.x); va[2] = bflo(wa.y); va[3] = bfhi(wa.y); va[4] = bflo(wa.z); va[5] = bfhi(wa.z); va[6] = bflo(wa.w); va[7] = bfhi(wa.w);
;     vb[0] = bflo(wb.x); vb[1] = bfhi(wb.x); vb[2] = bflo(wb.y); vb[3] = bfhi(wb.y); vb[4] = bflo(wb.z); vb[5] = bfhi(wb.z); vb[6] = bflo(wb.w); vb[7] = bfhi(wb.w);
;     if (hl >= 4) { const f32x2* rp = (const f32x2*)(a.ws + WS_ROPE) + pos * 32 + g * 8;
; #pragma unroll
;         for (int e = 0; e < 8; ++e) { const f32x2 cs = rp[e]; const float x1 = va[e], x2 = vb[e]; va[e] = x1 * cs.x - x2 * cs.y; vb[e] = x1 * cs.y + x2 * cs.x; } }
; }
.LBB0_142:
	s_or_b64 exec, exec, s[0:1]
	s_and_b32 s6, s15, 63
	s_lshl_b64 s[0:1], s[4:5], 12
	s_lshl_b32 s5, s6, 6
	v_bfe_u32 v21, v24, 2, 6
	s_or_b32 s0, s0, s5
	v_or_b32_e32 v4, s0, v21
	v_mov_b64_e32 v[2:3], s[22:23]
	v_mad_u64_u32 v[2:3], s[10:11], v4, s79, v[2:3]
	v_mad_i32_i24 v3, s1, v211, v3
	v_lshl_add_u64 v[2:3], v[0:1], 1, v[2:3]
	v_lshlrev_b32_e32 v0, 3, v24
	v_and_b32_e32 v22, 24, v0
	v_lshlrev_b32_e32 v0, 1, v22
	v_lshl_add_u64 v[6:7], v[2:3], 0, v[0:1]
	flat_load_dwordx4 v[2:5], v[6:7]
	flat_load_dwordx4 v[26:29], v[6:7] offset:64
	s_cmp_lt_u32 s28, 4
	s_waitcnt vmcnt(0) lgkmcnt(0)
	v_lshlrev_b32_e32 v18, 16, v2
	v_and_b32_e32 v19, 0xffff0000, v2
	v_lshlrev_b32_e32 v10, 16, v26
	v_and_b32_e32 v11, 0xffff0000, v26
	v_lshlrev_b32_e32 v14, 16, v3
	v_and_b32_e32 v15, 0xffff0000, v3
	v_lshlrev_b32_e32 v8, 16, v27
	v_and_b32_e32 v9, 0xffff0000, v27
	v_lshlrev_b32_e32 v12, 16, v4
	v_and_b32_e32 v13, 0xffff0000, v4
	v_lshlrev_b32_e32 v2, 16, v28
	v_and_b32_e32 v3, 0xffff0000, v28
	v_lshlrev_b32_e32 v4, 16, v5
	v_and_b32_e32 v5, 0xffff0000, v5
	v_lshlrev_b32_e32 v6, 16, v29
	v_and_b32_e32 v7, 0xffff0000, v29
	s_cbranch_scc1 .LBB0_116
	v_or_b32_e32 v16, s5, v21
	v_readlane_b32 s10, v254, 28
	v_lshlrev_b32_e32 v16, 8, v16
	v_mov_b32_e32 v17, v1
	v_readlane_b32 s11, v254, 29
	v_lshlrev_b32_e32 v26, 3, v22
	v_mov_b32_e32 v27, v1
	v_lshl_add_u64 v[16:17], s[10:11], 0, v[16:17]
	v_lshl_add_u64 v[30:31], v[16:17], 0, v[26:27]
	flat_load_dwordx4 v[26:29], v[30:31]
	flat_load_dwordx4 v[112:115], v[30:31] offset:16
	flat_load_dwordx4 v[116:119], v[30:31] offset:32
	flat_load_dwordx4 v[120:123], v[30:31] offset:48
	s_waitcnt vmcnt(0) lgkmcnt(0)
	v_mov_b32_e32 v32, v26
	v_mov_b32_e32 v33, v28
	v_mov_b32_e32 v28, v27
	v_pk_mul_f32 v[16:17], v[28:29], v[10:11]
	v_pk_mul_f32 v[10:11], v[32:33], v[10:11]
	v_pk_fma_f32 v[16:17], v[32:33], v[18:19], v[16:17] neg_lo:[0,0,1] neg_hi:[0,0,1]
	v_pk_fma_f32 v[10:11], v[28:29], v[18:19], v[10:11]
	v_mov_b32_e32 v26, v112
	v_mov_b32_e32 v27, v113
	v_mov_b32_e32 v28, v114
	v_mov_b32_e32 v29, v115
	v_mov_b32_e32 v18, v26
	v_mov_b32_e32 v19, v28
	v_mov_b32_e32 v28, v27
	v_pk_mul_f32 v[26:27], v[28:29], v[8:9]
	v_pk_mul_f32 v[8:9], v[18:19], v[8:9]
	v_pk_fma_f32 v[32:33], v[18:19], v[14:15], v[26:27] neg_lo:[0,0,1] neg_hi:[0,0,1]
	v_pk_fma_f32 v[8:9], v[28:29], v[14:15], v[8:9]
	v_mov_b32_e32 v26, v116
	v_mov_b32_e32 v27, v117
	v_mov_b32_e32 v28, v118
	v_mov_b32_e32 v29, v119
	v_mov_b32_e32 v14, v26
	v_mov_b32_e32 v15, v28
	v_mov_b32_e32 v28, v27
	v_pk_mul_f32 v[18:19], v[28:29], v[2:3]
	v_pk_mul_f32 v[2:3], v[14:15], v[2:3]
	v_pk_fma_f32 v[26:27], v[14:15], v[12:13], v[18:19] neg_lo:[0,0,1] neg_hi:[0,0,1]
	v_pk_fma_f32 v[2:3], v[28:29], v[12:13], v[2:3]
	v_mov_b32_e32 v12, v120
	v_mov_b32_e32 v13, v121
	v_mov_b32_e32 v14, v122
	v_mov_b32_e32 v15, v123
	v_mov_b32_e32 v30, v5
	v_mov_b32_e32 v31, v7
	v_mov_b32_e32 v28, v13
	v_pk_mul_f32 v[18:19], v[12:13], v[4:5]
	v_pk_mul_f32 v[28:29], v[28:29], v[6:7]
	v_pk_mul_f32 v[30:31], v[14:15], v[30:31]
	s_nop 0
	v_mov_b32_e32 v19, v30
	v_mov_b32_e32 v29, v31
	v_pk_add_f32 v[28:29], v[18:19], v[28:29] neg_lo:[0,1] neg_hi:[0,1]
	v_mov_b32_e32 v18, v13
	v_mov_b32_e32 v13, v14
	v_mov_b32_e32 v19, v15
	v_pk_mul_f32 v[6:7], v[12:13], v[6:7]
	v_mov_b32_e32 v14, v32
	v_pk_fma_f32 v[6:7], v[18:19], v[4:5], v[6:7]
	v_mov_b32_e32 v18, v16
	v_mov_b32_e32 v19, v17
	v_mov_b32_e32 v15, v33
	v_mov_b32_e32 v12, v26
	v_mov_b32_e32 v13, v27
	v_mov_b32_e32 v4, v28
	v_mov_b32_e32 v5, v29
	s_branch .LBB0_116

; __device__ __forceinline__ void r1_item(const Args& a, int L, int item, LAS unsigned char* lds) {
;     ...
;     } else { const int t2 = tid - 256, j = t2 >> 2, vg = t2 & 3; const int vcol = hl < 4 ? GV + hl * 128 : RV + (hl - 4) * 128;
;         const bf16_t* vp = proj + (R0 + j) * LD + vcol + vg * 32;
; #pragma unroll
;         for (int q = 0; q < 4; ++q) { const u32x4 w = *(const u32x4*)(vp + q * 8); const int v0 = vg * 32 + q * 8;
;             VT[(v0 + 0) * PT + j] = (bf16_t)(w.x & 0xffff); VT[(v0 + 1) * PT + j] = (bf16_t)(w.x >> 16); VT[(v0 + 2) * PT + j] = (bf16_t)(w.y & 0xffff); VT[(v0 + 3) * PT + j] = (bf16_t)(w.y >> 16);
;             VT[(v0 + 4) * PT + j] = (bf16_t)(w.z & 0xffff); VT[(v0 + 5) * PT + j] = (bf16_t)(w.z >> 16); VT[(v0 + 6) * PT + j] = (bf16_t)(w.w & 0xffff); VT[(v0 + 7) * PT + j] = (bf16_t)(w.w >> 16); } }
.LBB0_172:
	s_or_b64 exec, exec, s[0:1]
	s_and_b32 s15, s13, 63
	s_lshl_b64 s[10:11], s[4:5], 12
	s_lshl_b32 s5, s15, 6
	s_movk_i32 s0, 0xff
	s_or_b32 s10, s10, s5
	v_cmp_lt_i32_e32 vcc, s0, v34
	s_waitcnt lgkmcnt(0)
	s_barrier
	s_and_saveexec_b64 s[0:1], vcc
	s_xor_b64 s[0:1], exec, s[0:1]
	s_cbranch_execz .LBB0_174
	v_add_u32_e32 v0, 0xffffff00, v34
	v_lshrrev_b32_e32 v0, 2, v0
	s_lshl_b32 s24, s14, 7
	v_lshl_add_u64 v[2:3], s[10:11], 0, v[0:1]
	v_mov_b64_e32 v[4:5], s[22:23]
	s_or_b32 s30, s24, 0xe00
	s_addk_i32 s24, 0x1200
	v_mad_u64_u32 v[4:5], s[28:29], v2, s79, v[4:5]
	s_and_b64 s[28:29], s[8:9], exec
	v_mov_b32_e32 v2, v5
	s_cselect_b32 s24, s30, s24
	v_mad_u64_u32 v[2:3], s[28:29], v3, s79, v[2:3]
	v_mov_b32_e32 v5, v2
	s_lshl_b32 s24, s24, 1
	v_lshl_add_u64 v[2:3], v[4:5], 0, s[24:25]
	v_lshlrev_b32_e32 v4, 5, v34
	v_and_b32_e32 v8, 0x60, v4
	v_lshlrev_b32_e32 v4, 1, v8
	v_mov_b32_e32 v5, v1
	v_lshl_add_u64 v[6:7], v[2:3], 0, v[4:5]
	v_mul_u32_u24_e32 v2, 0x90, v8
	v_lshlrev_b32_e32 v0, 1, v0
	v_add3_u32 v0, 0, v2, v0
	flat_load_dwordx4 v[2:5], v[6:7]
	flat_load_dwordx4 v[112:115], v[6:7] offset:16
	flat_load_dwordx4 v[116:119], v[6:7] offset:32
	flat_load_dwordx4 v[120:123], v[6:7] offset:48
	s_waitcnt vmcnt(0) lgkmcnt(0)
	ds_write_b16 v0, v2 offset:32768
	ds_write_b16_d16_hi v0, v2 offset:32912
	ds_write_b16 v0, v3 offset:33056
	ds_write_b16_d16_hi v0, v3 offset:33200
	ds_write_b16 v0, v4 offset:33344
	ds_write_b16_d16_hi v0, v4 offset:33488
	ds_write_b16 v0, v5 offset:33632
	ds_write_b16_d16_hi v0, v5 offset:33776
	ds_write_b16 v0, v112 offset:33920
	ds_write_b16_d16_hi v0, v112 offset:34064
	ds_write_b16 v0, v113 offset:34208
	ds_write_b16_d16_hi v0, v113 offset:34352
	ds_write_b16 v0, v114 offset:34496
	ds_write_b16_d16_hi v0, v114 offset:34640
	ds_write_b16 v0, v115 offset:34784
	ds_write_b16_d16_hi v0, v115 offset:34928
	ds_write_b16 v0, v116 offset:35072
	ds_write_b16_d16_hi v0, v116 offset:35216
	ds_write_b16 v0, v117 offset:35360
	ds_write_b16_d16_hi v0, v117 offset:35504
	ds_write_b16 v0, v118 offset:35648
	ds_write_b16_d16_hi v0, v118 offset:35792
	ds_write_b16 v0, v119 offset:35936
	ds_write_b16_d16_hi v0, v119 offset:36080
	ds_write_b16 v0, v120 offset:36224
	ds_write_b16_d16_hi v0, v120 offset:36368
	ds_write_b16 v0, v121 offset:36512
	ds_write_b16_d16_hi v0, v121 offset:36656
	ds_write_b16 v0, v122 offset:36800
	ds_write_b16_d16_hi v0, v122 offset:36944
	ds_write_b16 v0, v123 offset:37088
	ds_write_b16_d16_hi v0, v123 offset:37232
